# select item setup: weight load issued first and waited with a counted vmcnt so the query-fragment loads stay in flight
# speedup vs baseline: 1.0049x; 1.0016x over previous
; __device__ __forceinline__ void dsa_select(const h16* PROJ, unsigned short* IDX, int* CNT, unsigned char* shm, unsigned* bar, unsigned xcc, unsigned xrank) {
;     ...
;         for (int k = 0; k < nrounds; ++k) {
;             const int it = k * total + ((k & 1) ? (total - 1 - rank) : rank);
;             if (it >= 256) continue;
;             const int tokbase = b * SEQ, t0 = it * 32 + wid * 4, tq = t0 + fq;
;             const int nch = ((it * 32 + 31) / 16 + 1 + 15) / 16;
; #pragma unroll
;             for (int i = 0; i < 16; ++i) myhist[lane + 64 * i] = 0u;
;             if (lane < 16) myctl[lane] = 0u;
;             h16x8 aq[2][2];
;             { const h16* qrow = PROJ + O_QI + (size_t)(tokbase + t0 + (fr >> 2)) * 512 + (fr & 3) * 64 + 8 * fq;
; #pragma unroll
;               for (int hh = 0; hh < 2; ++hh)
; #pragma unroll
;                   for (int kk = 0; kk < 2; ++kk) aq[hh][kk] = *(const h16x8*)(qrow + hh * 256 + kk * 32); }
;             float wv[8];
;             { const h16x8 w8 = *(const h16x8*)(PROJ + O_WI + (size_t)(tokbase + tq) * 8);
; #pragma unroll
;               for (int h = 0; h < 8; ++h) wv[h] = (float)w8[h] * 0.04419417382415922f; }
;             h16x2 wp[4];
; #pragma unroll
;             for (int h = 0; h < 4; ++h) { wp[h].x = (h16)wv[(h >> 1) * 4 + (h & 1) * 2]; wp[h].y = (h16)wv[(h >> 1) * 4 + (h & 1) * 2 + 1]; }
;             __builtin_amdgcn_s_waitcnt(0);
;             unsigned short* out = IDX + (size_t)(tokbase + tq) * 256;
;             unsigned* blkflag = (unsigned*)(shm + 131072 + 1024);
;             if (tid == 0) *blkflag = 0u;
.LBB0_172:
	s_bitcmp0_b32 s70, 0
	s_cselect_b64 vcc, -1, 0
	v_mul_lo_u32 v0, s70, v187
	v_cndmask_b32_e32 v1, v190, v188, vcc
	v_add_u32_e32 v0, v1, v0
	s_movk_i32 s4, 0xff
	v_cmp_lt_i32_e32 vcc, s4, v0
	s_cbranch_vccnz .LBB0_171
	ds_write2st64_b32 v130, v163, v163 offset1:1
	ds_write2st64_b32 v130, v163, v163 offset0:2 offset1:3
	ds_write2st64_b32 v130, v163, v163 offset0:4 offset1:5
	ds_write2st64_b32 v130, v163, v163 offset0:6 offset1:7
	ds_write2st64_b32 v130, v163, v163 offset0:8 offset1:9
	ds_write2st64_b32 v130, v163, v163 offset0:10 offset1:11
	ds_write2st64_b32 v130, v163, v163 offset0:12 offset1:13
	ds_write2st64_b32 v130, v163, v163 offset0:14 offset1:15
	s_and_saveexec_b64 s[58:59], s[44:45]
	ds_write_b32 v131, v163
	s_or_b64 exec, exec, s[58:59]
	s_waitcnt vmcnt(4)
	v_lshlrev_b32_e32 v20, 5, v0
	v_add_u32_e32 v0, v20, v129
	v_or_b32_e32 v192, v0, v126
	v_add_u32_e32 v0, v191, v0
	v_ashrrev_i32_e32 v1, 31, v0
	v_lshlrev_b64 v[0:1], 10, v[0:1]
	v_lshl_add_u64 v[12:13], v[96:97], 0, v[0:1]
	v_add_u32_e32 v104, s67, v192
	v_ashrrev_i32_e32 v105, 31, v104
	v_lshl_add_u64 v[16:17], v[104:105], 4, s[96:97]
	global_load_dwordx4 v[16:19], v[16:17], off
	global_load_dwordx4 v[0:3], v[12:13], off
	global_load_dwordx4 v[4:7], v[12:13], off offset:64
	global_load_dwordx4 v[8:11], v[12:13], off offset:512
	s_nop 0
	global_load_dwordx4 v[12:15], v[12:13], off offset:576
	s_waitcnt vmcnt(4) expcnt(0) lgkmcnt(0)
	s_and_saveexec_b64 s[58:59], s[46:47]
	s_cbranch_execz .LBB0_177
	v_readlane_b32 s4, v254, 45
	s_nop 1
	v_mov_b32_e32 v21, s4
	ds_write_b32 v21, v163
